# diff-attention pairs: each unit of a (q,k)-pair sums half of every row in the steady tiles (16 adds/step instead of 32), O leaves unnormalised, combine phase divides by the pair total; no-rescale boun
# speedup vs baseline: 1.0125x; 1.0100x over previous
;   int tid_=threadIdx.x; asm volatile("":"+v"(tid_)); const int tid=tid_,lane=tid&63,r32=lane&31,hi=lane>>5; const int wid=__builtin_amdgcn_readfirstlane(tid>>6);
;   const int q0=qb*QB;
;   const bf16*Qw=Q+(long)(q0+wid*QBLK)*DM;
;   const bf16*Kh=K+(long)t0*KVBLK*DM,*Vh=V+(long)t0*KVBLK*DM;
;   const unsigned lds0=(unsigned)(uintptr_t)shm;
;   float*wsf=(float*)(shm+LDS_WS)+wid*64;
;   const bf16*ksrc=Kh+(long)lane*DM+wid*8;
;   const bf16*vsrc=Vh+(long)(16*(wid&3)+(lane>>2))*DM+(wid>>2)*32+(lane&3)*8;
;   const unsigned kdst=lds0+LDS_K+wid*1024, vdst=lds0+LDS_V+wid*1024;
;     ...
;   const int vb0=(int)(lds0+LDS_V)+((lane>>4)&1)*32+(lane&3)*8+(4*hi+((lane&15)>>2))*64;
;   const char*Kbase=shm+LDS_K; bf16x8 kf[8];
;   const lds_cptr shm3=(lds_cptr)shm; const lds_cptr kp0=shm3+LDS_K+hi*1024+r32*16; const lds_cptr vp0=shm3+LDS_V+((lane>>4)&1)*32+(lane&3)*8+(4*hi+((lane&15)>>2))*64;
;   const int NT=(q0+QB)/KVBLK-t0;
;   bf16x8 qr[4]; unsigned long long sel=0ull;
;   const bf16*Qrow=Qw+(long)r32*DM;
;   if(MODE==3){ const int p_=wid*QBLK+r32; const long trow_=list?(long)list[p_<len?p_:len-1]:(long)(q0+p_); Qrow=Q+trow_*DM; }
;   if(MODE==1){
;     #pragma unroll
;     for(int d0=0;d0<4;++d0)qr[d0]=*reinterpret_cast<const bf16x8*>(&Qrow[d0*16+hi*8]);
;     float*km=(float*)(shm+86016);
;     #pragma unroll
;     for(int i=0;i<8;++i){const int e=tid+512*i; km[e]=(ksum[e]+ksum[e+4*64*64])*(1.0f/256.0f);}
;     asm volatile("s_waitcnt vmcnt(0) lgkmcnt(0)\n\ts_barrier":::"memory");
;     float qf[32];
;     #pragma unroll
;     for(int d0=0;d0<4;++d0)
;       #pragma unroll
;       for(int j=0;j<8;++j)qf[d0*8+j]=__uint_as_float(((unsigned)(unsigned short)qr[d0][j])<<16);
;     float t1=-INFINITY,t2=-INFINITY,t3=-INFINITY; int i1=-1,i2=-1,i3=-1;
;     for(int b=0;b<qb;++b){
;       const float*kr=km+b*64+hi*8; float g=0.f;
;       #pragma unroll
;       for(int d0=0;d0<4;++d0)
;         #pragma unroll
;         for(int j=0;j<8;++j)g+=qf[d0*8+j]*kr[d0*16+j];
;       g+=__shfl_xor(g,32);
;       if(g>t3){ if(g>t2){ t3=t2;i3=i2; if(g>t1){t2=t1;i2=i1;t1=g;i1=b;} else {t2=g;i2=b;} } else {t3=g;i3=b;} }
;     }
;     if(i1>=0)sel|=1ull<<i1; if(i2>=0)sel|=1ull<<i2; if(i3>=0)sel|=1ull<<i3;
;   }
;   DMA_K(0,0);DMA_V(0,0);DMA_K(1,SLOTB);
;   if(MODE!=1){
;     #pragma unroll
;     for(int d0=0;d0<4;++d0)qr[d0]=*reinterpret_cast<const bf16x8*>(&Qrow[d0*16+hi*8]);
;   }
.LBB0_1204:
	s_andn2_b64 vcc, exec, s[0:1]
	s_cbranch_vccnz .LBB0_1075
	s_ashr_i32 s0, s69, 31
	s_lshr_b32 s0, s0, 28
	s_add_i32 s1, s69, s0
	s_ashr_i32 s12, s1, 4
	s_and_b32 s1, s1, -16
	s_sub_i32 s4, s69, s1
	s_and_b32 s32, s32, 1
	s_lshl_b32 s0, s4, 8
	s_or_b32 s32, s32, s0
	s_lshl_b32 s0, s12, 16
	s_or_b32 s32, s32, s0
	s_mov_b32 s82, 0x41000000
	s_bitcmp1_b32 s32, 0
	s_cselect_b32 s82, 0x7f800000, s82
	v_mov_b32_e32 v223, 0
	s_ashr_i32 s30, s4, 2
	s_lshl_b32 s2, s30, 7
	s_ashr_i32 s3, s2, 31
	s_sub_i32 s0, 63, s12
	s_lshl_b64 s[20:21], s[2:3], 1
	s_add_u32 s1, s60, s20
	s_addc_u32 s2, s61, s21
	s_bfe_u32 s31, s4, 0x10001
	s_lshl_b32 s3, s31, 7
	s_add_u32 s1, s1, s3
	s_addc_u32 s2, s2, 0
	s_add_u32 s5, s62, s20
	s_addc_u32 s8, s63, s21
	s_add_u32 s10, s5, s3
	s_addc_u32 s11, s8, 0
	s_add_u32 s3, s64, s20
	s_addc_u32 s8, s65, s21
	s_lshl_b32 s5, s4, 6
	s_and_b32 s9, s5, 64
	s_lshl_b32 s34, s9, 1
	v_mov_b32_e32 v84, v230
	s_add_u32 s22, s3, s34
	s_addc_u32 s23, s8, 0
	v_readfirstlane_b32 s3, v84
	s_ashr_i32 s28, s3, 6
	s_lshl_b32 s8, s0, 8
	s_lshl_b32 s9, s28, 5
	v_and_b32_e32 v200, 63, v84
	s_add_i32 s29, s9, s8
	s_mul_i32 s24, s29, 0x1600
	v_mul_u32_u24_e32 v0, 0xb00, v200
	s_mul_hi_i32 s13, s29, 0x1600
	s_add_u32 s24, s1, s24
	v_lshlrev_b32_e32 v112, 1, v0
	s_addc_u32 s25, s2, s13
	v_lshl_add_u64 v[0:1], s[10:11], 0, v[112:113]
	s_lshl_b32 s10, s28, 3
	s_ashr_i32 s11, s10, 31
	v_lshl_add_u64 v[80:81], s[10:11], 1, v[0:1]
	s_lshl_b32 s1, s28, 4
	v_bfe_u32 v0, v84, 2, 4
	v_and_or_b32 v0, s1, 48, v0
	v_mul_u32_u24_e32 v0, 0xb00, v0
	v_lshlrev_b32_e32 v182, 1, v0
	v_mov_b32_e32 v183, v113
	s_ashr_i32 s1, s3, 3
	v_lshl_add_u64 v[0:1], s[22:23], 0, v[182:183]
	s_and_b32 s22, s1, 0xffffffe0
	s_ashr_i32 s23, s22, 31
	v_lshlrev_b32_e32 v201, 3, v84
	s_lshl_b32 s2, s28, 10
	v_and_b32_e32 v204, 24, v201
	s_cmp_lg_u32 0, -1
	v_and_b32_e32 v202, 31, v84
	v_lshl_add_u64 v[0:1], s[22:23], 1, v[0:1]
	v_lshlrev_b32_e32 v2, 1, v204
	v_mov_b32_e32 v3, v113
	s_cselect_b32 s1, 0, 0
	v_bfe_u32 v203, v84, 5, 1
	v_lshl_add_u64 v[82:83], v[0:1], 0, v[2:3]
	s_add_i32 s69, s2, s1
	v_mul_u32_u24_e32 v0, 0x1600, v202
	v_mov_b32_e32 v1, v113
	s_mov_b32 s1, m0
	s_mov_b32 m0, s69
	s_nop 0
	global_load_lds_dwordx4 v[80:81], off
	s_mov_b32 m0, s1
	s_add_i32 s70, s69, 0x6000
	v_lshl_add_u64 v[0:1], s[24:25], 0, v[0:1]
	s_mov_b32 s1, m0
	s_mov_b32 m0, s70
	s_nop 0
	global_load_lds_dwordx4 v[82:83], off
	s_mov_b32 m0, s1
	v_lshlrev_b32_e32 v190, 4, v203
	v_mov_b32_e32 v191, v113
	v_lshl_add_u64 v[2:3], v[80:81], 0, s[78:79]
	s_add_i32 s1, s69, 0x2000
	s_mov_b32 s13, m0
	s_mov_b32 m0, s1
	s_nop 0
	global_load_lds_dwordx4 v[2:3], off
	s_mov_b32 m0, s13
	v_lshl_add_u64 v[14:15], v[0:1], 0, v[190:191]
	flat_load_dwordx4 v[134:137], v[14:15]
	flat_load_dwordx4 v[122:125], v[14:15] offset:32
	flat_load_dwordx4 v[118:121], v[14:15] offset:64
	flat_load_dwordx4 v[114:117], v[14:15] offset:96
	v_mov_b32_e32 v0, v113
	v_mov_b32_e32 v1, v113
	v_mov_b32_e32 v2, v113
	v_mov_b32_e32 v3, v113
	v_mov_b32_e32 v4, v113
	v_mov_b32_e32 v5, v113
	v_mov_b32_e32 v6, v113
	v_mov_b32_e32 v7, v113
	v_mov_b32_e32 v8, v113
	v_mov_b32_e32 v9, v113
	v_mov_b32_e32 v10, v113
	v_mov_b32_e32 v11, v113
	v_mov_b32_e32 v12, v113
	v_mov_b32_e32 v13, v113
	v_mov_b32_e32 v14, v113
	v_mov_b32_e32 v15, v113
	v_lshlrev_b32_e32 v16, 10, v203
	v_lshlrev_b32_e32 v17, 4, v202
	v_add3_u32 v210, 0, v16, v17
	v_lshl_add_u64 v[16:17], v[80:81], 0, s[94:95]
	s_add_i32 s1, s69, 0x4000
	s_mov_b32 s13, m0
	s_mov_b32 m0, s1
	s_nop 0
	global_load_lds_dwordx4 v[16:17], off
	s_mov_b32 m0, s13
	s_waitcnt vmcnt(3) lgkmcnt(0)
	s_barrier
	ds_read_b128 v[32:35], v210
	s_cmp_lg_u32 s0, 0
	s_cselect_b64 s[0:1], -1, 0
	v_lshlrev_b32_e32 v205, 2, v203
	v_or_b32_e32 v208, s9, v202
	s_and_b64 vcc, exec, s[0:1]
	s_waitcnt vmcnt(0) lgkmcnt(0)
	v_mfma_f32_32x32x16_bf16 v[16:31], v[32:35], v[134:137], v[0:15]
	ds_read_b128 v[32:35], v210 offset:512
	s_waitcnt lgkmcnt(0)
	v_mfma_f32_32x32x16_bf16 v[0:15], v[32:35], v[134:137], v[0:15]
	ds_read_b128 v[32:35], v210 offset:2048
	s_waitcnt lgkmcnt(0)
	v_mfma_f32_32x32x16_bf16 v[16:31], v[32:35], v[122:125], v[16:31]
	ds_read_b128 v[32:35], v210 offset:2560
	s_waitcnt lgkmcnt(0)
	v_mfma_f32_32x32x16_bf16 v[0:15], v[32:35], v[122:125], v[0:15]
	ds_read_b128 v[32:35], v210 offset:4096
	s_waitcnt lgkmcnt(0)
	v_mfma_f32_32x32x16_bf16 v[16:31], v[32:35], v[118:121], v[16:31]
	ds_read_b128 v[32:35], v210 offset:4608
	s_waitcnt lgkmcnt(0)
	v_mfma_f32_32x32x16_bf16 v[0:15], v[32:35], v[118:121], v[0:15]
	ds_read_b128 v[32:35], v210 offset:6144
	s_waitcnt lgkmcnt(0)
	v_mfma_f32_32x32x16_bf16 v[16:31], v[32:35], v[114:117], v[16:31]
	ds_read_b128 v[32:35], v210 offset:6656
	s_waitcnt lgkmcnt(0)
	v_mfma_f32_32x32x16_bf16 v[0:15], v[32:35], v[114:117], v[0:15]
	s_nop 15
	s_nop 7
	s_cbranch_vccnz .LBB0_1207
; __device__ __forceinline__ void cmask(f32x16&p0,f32x16&p1,int jb,int qrel,int hi){
;   const float NEG=NEGV; int kb=64*jb+4*hi;
;   #pragma unroll
;   for(int r=0;r<16;++r){int kv=kb+(r&3)+8*(r>>2); if(kv>qrel)p0[r]=NEG; if(kv+32>qrel)p1[r]=NEG;}
; }
	v_or_b32_e32 v32, 32, v205
	v_cmp_le_i32_e32 vcc, v32, v208
	v_or_b32_e32 v32, 33, v205
	s_nop 7
	v_cndmask_b32_e32 v0, v240, v0, vcc
	v_cmp_lt_i32_e32 vcc, v205, v208
	s_nop 1
	v_cndmask_b32_e32 v17, v240, v17, vcc
	v_cmp_le_i32_e32 vcc, v205, v208
	s_nop 1
	v_cndmask_b32_e32 v16, v240, v16, vcc
	v_cmp_le_i32_e32 vcc, v32, v208
	v_or_b32_e32 v32, 2, v205
	s_nop 0
	v_cndmask_b32_e32 v1, v240, v1, vcc
	v_cmp_le_i32_e32 vcc, v32, v208
	v_or_b32_e32 v32, 34, v205
	s_nop 0
	v_cndmask_b32_e32 v18, v240, v18, vcc
	v_cmp_le_i32_e32 vcc, v32, v208
	v_or_b32_e32 v32, 3, v205
	s_nop 0
	v_cndmask_b32_e32 v2, v240, v2, vcc
	v_cmp_le_i32_e32 vcc, v32, v208
	v_or_b32_e32 v32, 35, v205
	s_nop 0
	v_cndmask_b32_e32 v19, v240, v19, vcc
	v_cmp_le_i32_e32 vcc, v32, v208
	v_or_b32_e32 v32, 8, v205
	s_nop 0
	v_cndmask_b32_e32 v3, v240, v3, vcc
	v_cmp_le_i32_e32 vcc, v32, v208
	v_or_b32_e32 v32, 40, v205
	s_nop 0
	v_cndmask_b32_e32 v20, v240, v20, vcc
	v_cmp_le_i32_e32 vcc, v32, v208
	v_or_b32_e32 v32, 9, v205
	s_nop 0
	v_cndmask_b32_e32 v4, v240, v4, vcc
	v_cmp_le_i32_e32 vcc, v32, v208
	v_or_b32_e32 v32, 41, v205
	s_nop 0
	v_cndmask_b32_e32 v21, v240, v21, vcc
	v_cmp_le_i32_e32 vcc, v32, v208
	v_or_b32_e32 v32, 10, v205
	s_nop 0
	v_cndmask_b32_e32 v5, v240, v5, vcc
	v_cmp_le_i32_e32 vcc, v32, v208
	v_or_b32_e32 v32, 42, v205
	s_nop 0
	v_cndmask_b32_e32 v22, v240, v22, vcc
	v_cmp_le_i32_e32 vcc, v32, v208
	v_or_b32_e32 v32, 11, v205
	s_nop 0
	v_cndmask_b32_e32 v6, v240, v6, vcc
	v_cmp_le_i32_e32 vcc, v32, v208
	v_or_b32_e32 v32, 43, v205
	s_nop 0
	v_cndmask_b32_e32 v23, v240, v23, vcc
	v_cmp_le_i32_e32 vcc, v32, v208
	v_or_b32_e32 v32, 16, v205
	s_nop 0
	v_cndmask_b32_e32 v7, v240, v7, vcc
	v_cmp_le_i32_e32 vcc, v32, v208
	v_or_b32_e32 v32, 48, v205
	s_nop 0
	v_cndmask_b32_e32 v24, v240, v24, vcc
	v_cmp_le_i32_e32 vcc, v32, v208
	v_or_b32_e32 v32, 17, v205
	s_nop 0
	v_cndmask_b32_e32 v8, v240, v8, vcc
	v_cmp_le_i32_e32 vcc, v32, v208
	v_or_b32_e32 v32, 49, v205
	s_nop 0
	v_cndmask_b32_e32 v25, v240, v25, vcc
	v_cmp_le_i32_e32 vcc, v32, v208
	v_or_b32_e32 v32, 18, v205
	s_nop 0
	v_cndmask_b32_e32 v9, v240, v9, vcc
	v_cmp_le_i32_e32 vcc, v32, v208
	v_or_b32_e32 v32, 50, v205
	s_nop 0
	v_cndmask_b32_e32 v26, v240, v26, vcc
	v_cmp_le_i32_e32 vcc, v32, v208
	v_or_b32_e32 v32, 19, v205
	s_nop 0
	v_cndmask_b32_e32 v10, v240, v10, vcc
	v_cmp_le_i32_e32 vcc, v32, v208
	v_or_b32_e32 v32, 51, v205
	s_nop 0
	v_cndmask_b32_e32 v27, v240, v27, vcc
	v_cmp_le_i32_e32 vcc, v32, v208
	v_or_b32_e32 v32, 24, v205
	s_nop 0
	v_cndmask_b32_e32 v11, v240, v11, vcc
	v_cmp_le_i32_e32 vcc, v32, v208
	v_or_b32_e32 v32, 56, v205
	s_nop 0
	v_cndmask_b32_e32 v28, v240, v28, vcc
	v_cmp_le_i32_e32 vcc, v32, v208
	v_or_b32_e32 v32, 25, v205
	s_nop 0
	v_cndmask_b32_e32 v12, v240, v12, vcc
	v_cmp_le_i32_e32 vcc, v32, v208
	v_or_b32_e32 v32, 57, v205
	s_nop 0
	v_cndmask_b32_e32 v29, v240, v29, vcc
	v_cmp_le_i32_e32 vcc, v32, v208
	v_or_b32_e32 v32, 26, v205
	s_nop 0
	v_cndmask_b32_e32 v13, v240, v13, vcc
	v_cmp_le_i32_e32 vcc, v32, v208
	v_or_b32_e32 v32, 58, v205
	s_nop 0
	v_cndmask_b32_e32 v30, v240, v30, vcc
	v_cmp_le_i32_e32 vcc, v32, v208
	v_or_b32_e32 v32, 27, v205
	s_nop 0
	v_cndmask_b32_e32 v14, v240, v14, vcc
	v_cmp_le_i32_e32 vcc, v32, v208
	v_or_b32_e32 v32, 59, v205
	s_nop 0
	v_cndmask_b32_e32 v31, v240, v31, vcc
	v_cmp_le_i32_e32 vcc, v32, v208
	s_nop 1
	v_cndmask_b32_e32 v15, v240, v15, vcc
; __device__ __forceinline__ float max3f(float a,float b,float c){float r;asm("v_max3_f32 %0, %1, %2, %3":"=v"(r):"v"(a),"v"(b),"v"(c));return r;}
; __device__ __forceinline__ float max2f(float a,float b){float r;asm("v_max_f32_e32 %0, %1, %2":"=v"(r):"v"(a),"v"(b));return r;}
; #define WAIT_BAR(N) asm volatile("s_waitcnt vmcnt(" #N ") lgkmcnt(0)\n\ts_barrier":::"memory")
;   #define DMA_K(t,slot) glds16(ksrc+(long)(t)*KVBLK*DM,(unsigned)__builtin_amdgcn_readfirstlane(kdst+(slot)))
;   #define DMA_V(t,slot) glds16(vsrc+(long)(t)*KVBLK*DM,(unsigned)__builtin_amdgcn_readfirstlane(vdst+(slot)))
;   #define CMASK(P0,P1,t) do{int jb_=(t)-(NT-4); if(MODE==3){ if(!list&&jb_>=0)cmask(P0,P1,jb_,qrel,hi); } else if(MODE==2){swamask(P0,P1,jb_,qrel,hi);} else if(jb_>=0){cmask(P0,P1,jb_,qrel,hi);} else if(MODE==1){mobamask(P0,P1,sel,(t)>>2);} }while(0)
;   #define START(P0,P1) do{ const float rm=rowmax(P0,P1); resc=false; \
;     { const float dl=rm; mhat=fadd_s(mhat,dl); \
;       _Pragma("unroll") for(int r=0;r<16;++r){P0[r]=fsub_s(P0[r],dl);P1[r]=fsub_s(P1[r],dl);} \
;       _Pragma("unroll") for(int r=0;r<16;++r)negm[r]=-mhat; asm volatile("":"+v"(negm)); } \
;     _Pragma("unroll") for(int r=0;r<16;++r)P0[r]=__builtin_amdgcn_exp2f(P0[r]); }while(0)
;   #define ROT() do{sl_prev=sl_cur;sl_cur=sl_next;sl_next=(sl_next==(NSLOT-1)*SLOTB)?0:sl_next+SLOTB;}while(0)
;   #define CMASK(P0,P1,t) do{ if(MODE==1){mobamask(P0,P1,sel,(t)>>2);} }while(0)
; __device__ __forceinline__ float rowmax(const f32x16&p0,const f32x16&p1){
;   float a=max3f(p0[0],p0[1],p1[0]),b=max3f(p0[2],p0[3],p1[1]);a=max3f(a,p1[2],p1[3]);
;   #pragma unroll
;   for(int r=4;r<16;r+=4){a=max3f(a,p0[r],p0[r+1]);b=max3f(b,p0[r+2],p0[r+3]);a=max3f(a,p1[r],p1[r+1]);b=max3f(b,p1[r+2],p1[r+3]);}
;   const float m=max2f(a,b);
;   auto rr=__builtin_amdgcn_permlane32_swap(__float_as_uint(m),__float_as_uint(m),false,false);
;   return max2f(__uint_as_float(rr[0]),__uint_as_float(rr[1]));
; }
;     ...
;   f32x16 pA0,pA1,pB0,pB1;
;   int sl_prev=0,sl_cur=0,sl_next=SLOTB;
;     ...
;   DMA_K(2,2*SLOTB);
;   WAIT_BAR(3);
;   qkt(pA0,pA1,Kbase,qr,negm,r32,hi);asm volatile("s_nop 15\n\ts_nop 7":"+v"(pA0),"+v"(pA1));CMASK(pA0,pA1,0);
;   START(pA0,pA1);
;   _Pragma("unroll") for(int r=0;r<16;++r)pA1[r]=__builtin_amdgcn_exp2f(pA1[r]);
;   WAIT_BAR(0);
;   DMA_K(3,0);DMA_V(1,SLOTB);
;   ROT();
;   kload8(kf,kp0+sl_cur);
;   WAIT_BAR(2);
.LBB0_1207:
	v_lshlrev_b32_e32 v32, 1, v84
	v_and_b32_e32 v206, 32, v32
	v_lshlrev_b32_e32 v32, 4, v84
	v_and_b32_e32 v32, 0xc0, v32
	v_lshl_or_b32 v191, v203, 8, v32
	v_add_u32_e32 v32, 0, v206
	v_add3_u32 v211, v32, v204, v191
	v_max3_f32 v32, v16, v17, v0
	v_max3_f32 v33, v18, v19, v1
	s_and_b32 s9, s3, 0x3fffffc0
	v_max3_f32 v32, v32, v2, v3
	v_max3_f32 v33, v33, v22, v23
	s_addk_i32 s8, 0x100
	v_max3_f32 v32, v32, v20, v21
	v_max3_f32 v33, v33, v6, v7
	s_lshl_b32 s9, s9, 2
	v_max3_f32 v32, v32, v4, v5
	v_max3_f32 v33, v33, v26, v27
	s_add_i32 s35, s9, 0
	v_max3_f32 v32, v32, v24, v25
	v_max3_f32 v33, v33, v10, v11
	s_lshr_b32 s71, s8, 6
	v_max3_f32 v32, v32, v8, v9
	v_max3_f32 v33, v33, v30, v31
	s_mov_b64 s[8:9], 0x108000
	v_max3_f32 v32, v32, v28, v29
	v_max3_f32 v33, v33, v14, v15
	s_cmp_lg_u32 0, -1
	v_max3_f32 v32, v32, v12, v13
	s_mov_b32 s3, 1
	v_max_f32_e32 v32, v32, v33
	s_mov_b32 s13, 0
	v_mov_b32_e32 v33, v32
	s_nop 1
	v_permlane32_swap_b32_e32 v32, v33
	v_max_f32_e32 v32, v32, v33
	v_lshl_add_u32 v207, v202, 2, s35
	v_add_f32_e32 v209, v113, v32
	v_sub_f32_e32 v16, v16, v32
	v_sub_f32_e32 v0, v0, v32
	v_sub_f32_e32 v17, v17, v32
	v_sub_f32_e32 v1, v1, v32
	v_sub_f32_e32 v18, v18, v32
	v_sub_f32_e32 v2, v2, v32
	v_sub_f32_e32 v19, v19, v32
	v_sub_f32_e32 v3, v3, v32
	v_sub_f32_e32 v20, v20, v32
	v_sub_f32_e32 v4, v4, v32
	v_sub_f32_e32 v21, v21, v32
	v_sub_f32_e32 v5, v5, v32
	v_sub_f32_e32 v22, v22, v32
	v_sub_f32_e32 v6, v6, v32
	v_sub_f32_e32 v23, v23, v32
	v_sub_f32_e32 v7, v7, v32
	v_sub_f32_e32 v24, v24, v32
	v_sub_f32_e32 v8, v8, v32
	v_sub_f32_e32 v25, v25, v32
	v_sub_f32_e32 v9, v9, v32
	v_sub_f32_e32 v26, v26, v32
	v_sub_f32_e32 v10, v10, v32
	v_sub_f32_e32 v27, v27, v32
	v_sub_f32_e32 v11, v11, v32
	v_sub_f32_e32 v28, v28, v32
	v_sub_f32_e32 v12, v12, v32
	v_sub_f32_e32 v29, v29, v32
	v_sub_f32_e32 v13, v13, v32
	v_sub_f32_e32 v30, v30, v32
	v_sub_f32_e32 v14, v14, v32
	v_sub_f32_e32 v31, v31, v32
	v_sub_f32_e32 v15, v15, v32
	s_nop 0
	v_xor_b32_e32 v32, 0x80000000, v209
	v_mov_b32_e32 v33, v32
	v_mov_b32_e32 v34, v32
	v_mov_b32_e32 v35, v32
	v_mov_b32_e32 v36, v32
	v_mov_b32_e32 v37, v32
	v_mov_b32_e32 v38, v32
	v_mov_b32_e32 v39, v32
	v_mov_b32_e32 v40, v32
	v_mov_b32_e32 v41, v32
	v_mov_b32_e32 v42, v32
	v_mov_b32_e32 v43, v32
	v_mov_b32_e32 v44, v32
	v_mov_b32_e32 v45, v32
	v_mov_b32_e32 v46, v32
	v_mov_b32_e32 v47, v32
	s_waitcnt vmcnt(0) lgkmcnt(0)
	s_barrier
	v_exp_f32_e32 v48, v0
	v_exp_f32_e32 v49, v1
	v_lshl_add_u64 v[0:1], v[80:81], 0, s[8:9]
	s_mov_b32 s8, m0
	s_mov_b32 m0, s69
	s_nop 0
	global_load_lds_dwordx4 v[0:1], off
	s_mov_b32 m0, s8
	s_cselect_b32 s8, 0, 0
	s_add_i32 s2, s8, s2
	v_lshl_add_u64 v[0:1], v[82:83], 0, s[78:79]
	s_add_i32 s2, s2, 0x8000
	s_mov_b32 s8, m0
	s_mov_b32 m0, s2
	s_nop 0
	global_load_lds_dwordx4 v[0:1], off
	s_mov_b32 m0, s8
	ds_read_b128 v[174:177], v210 offset:8192
	ds_read_b128 v[170:173], v210 offset:8704
	ds_read_b128 v[166:169], v210 offset:10240
	ds_read_b128 v[162:165], v210 offset:10752
	ds_read_b128 v[158:161], v210 offset:12288
	ds_read_b128 v[154:157], v210 offset:12800
	ds_read_b128 v[150:153], v210 offset:14336
	ds_read_b128 v[146:149], v210 offset:14848
	v_exp_f32_e32 v64, v16
	v_exp_f32_e32 v65, v17
	v_exp_f32_e32 v66, v18
	v_exp_f32_e32 v67, v19
	v_exp_f32_e32 v68, v20
	v_exp_f32_e32 v69, v21
	v_exp_f32_e32 v70, v22
	v_exp_f32_e32 v71, v23
	v_exp_f32_e32 v72, v24
	v_exp_f32_e32 v73, v25
	v_exp_f32_e32 v74, v26
	v_exp_f32_e32 v75, v27
	v_exp_f32_e32 v76, v28
	v_exp_f32_e32 v77, v29
	v_exp_f32_e32 v78, v30
	v_exp_f32_e32 v79, v31
	v_exp_f32_e32 v50, v2
	v_exp_f32_e32 v51, v3
	v_exp_f32_e32 v52, v4
	v_exp_f32_e32 v53, v5
	v_exp_f32_e32 v54, v6
	v_exp_f32_e32 v55, v7
	v_exp_f32_e32 v56, v8
	v_exp_f32_e32 v57, v9
	v_exp_f32_e32 v58, v10
	v_exp_f32_e32 v59, v11
	v_exp_f32_e32 v60, v12
	v_exp_f32_e32 v61, v13
	v_exp_f32_e32 v62, v14
	v_exp_f32_e32 v63, v15
	s_waitcnt vmcnt(2) lgkmcnt(0)
	s_barrier
	v_and_b32_e32 v0, 3, v84
	s_andn2_b64 vcc, exec, s[0:1]
	v_cmp_gt_u32_e64 s[8:9], 32, v200
	v_lshlrev_b32_e32 v184, 4, v0
	s_cbranch_vccnz .LBB0_1223
	s_and_b32 s0, s4, 1
	s_lshl_b32 s2, s0, 7
	s_lshl_b64 s[0:1], s[22:23], 1
	s_add_u32 s0, s0, s2
	v_mov_b32_e32 v185, v113
	s_addc_u32 s1, s1, 0
	v_lshl_add_u64 v[0:1], s[0:1], 0, v[184:185]
	s_and_b32 s2, s5, 0x80
	s_lshl_b64 s[0:1], s[10:11], 1
	s_add_u32 s0, s2, s0
	v_mov_b32_e32 v183, v113
	s_addc_u32 s1, 0, s1
	v_lshl_add_u64 v[0:1], v[0:1], 0, v[182:183]
	s_add_u32 s0, s16, s0
	v_mov_b32_e32 v16, v113
	v_mov_b32_e32 v17, v113
	v_lshl_add_u64 v[186:187], s[16:17], 0, v[0:1]
	s_addc_u32 s1, s17, s1
	v_mov_b32_e32 v18, v113
	v_mov_b32_e32 v19, v113
	v_mov_b32_e32 v20, v113
	v_mov_b32_e32 v21, v113
	v_mov_b32_e32 v22, v113
	v_mov_b32_e32 v23, v113
	v_mov_b32_e32 v24, v113
	v_mov_b32_e32 v25, v113
	v_mov_b32_e32 v26, v113
	v_mov_b32_e32 v27, v113
	v_mov_b32_e32 v28, v113
	v_mov_b32_e32 v29, v113
	v_mov_b32_e32 v30, v113
	v_mov_b32_e32 v31, v113
	v_mov_b64_e32 v[0:1], v[16:17]
	s_mov_b32 s75, 6
	v_lshl_add_u64 v[188:189], s[0:1], 0, v[112:113]
	s_mov_b32 s0, 0
	s_movk_i32 s13, 0x4000
	s_movk_i32 s24, 0x2000
	v_mov_b32_e32 v222, 0
	v_mov_b64_e32 v[2:3], v[18:19]
	v_mov_b64_e32 v[4:5], v[20:21]
	v_mov_b64_e32 v[6:7], v[22:23]
	v_mov_b64_e32 v[8:9], v[24:25]
	v_mov_b64_e32 v[10:11], v[26:27]
	v_mov_b64_e32 v[12:13], v[28:29]
	v_mov_b64_e32 v[14:15], v[30:31]
	s_bitcmp1_b32 s32, 0
	s_cbranch_scc1 .Lfb_pre

.Lfb_pre:
	v_lshl_add_u64 v[188:189], v[188:189], 0, s[20:21]
	v_lshl_add_u64 v[186:187], v[186:187], 0, s[20:21]
	s_mov_b64 s[0:1], 0x5d60e00
	v_lshl_add_u64 v[188:189], v[188:189], 0, s[0:1]
	s_mov_b64 s[0:1], 0x5cb1200
	v_lshl_add_u64 v[186:187], v[186:187], 0, s[0:1]
	s_nop 0
	v_readfirstlane_b32 s2, v188
	v_readfirstlane_b32 s3, v189
	v_readfirstlane_b32 s26, v186
	v_readfirstlane_b32 s27, v187
	s_nop 1
	v_subrev_u32_e32 v188, s2, v188
	v_subrev_u32_e32 v186, s26, v186
	s_mov_b32 s0, 0
	s_bitcmp1_b32 s32, 8
	s_cbranch_scc1 .Lfb_odd
.Lfb_even:
	v_mfma_f32_32x32x16_bf16 v[96:111], v[174:177], v[134:137], v[32:47]
	v_add_u32_e32 v183, s0, v211
	ds_read_b64_tr_b16 v[178:179], v183 offset:24576
	ds_read_b64_tr_b16 v[180:181], v183 offset:25088
	v_add_f32_e32 v222, v64, v222
	v_add_f32_e32 v222, v65, v222
	v_add_f32_e32 v222, v66, v222
	v_add_f32_e32 v222, v67, v222
	v_add_f32_e32 v222, v68, v222
	v_add_f32_e32 v222, v69, v222
	v_cvt_pk_bf16_f32 v142, v64, v65
	v_cvt_pk_bf16_f32 v143, v66, v67
	ds_read_b64_tr_b16 v[174:175], v183 offset:28672
	ds_read_b64_tr_b16 v[176:177], v183 offset:29184
	v_add_f32_e32 v222, v70, v222
	v_mfma_f32_32x32x16_bf16 v[80:95], v[170:173], v[134:137], v[32:47]
	v_add_f32_e32 v222, v71, v222
	v_add_f32_e32 v222, v72, v222
	v_add_f32_e32 v222, v73, v222
	v_cvt_pk_bf16_f32 v144, v68, v69
	v_cvt_pk_bf16_f32 v145, v70, v71
	ds_read_b64_tr_b16 v[64:65], v183 offset:25600
	ds_read_b64_tr_b16 v[66:67], v183 offset:26112
	v_mfma_f32_32x32x16_bf16 v[96:111], v[166:169], v[122:125], v[96:111]
	v_add_f32_e32 v222, v74, v222
	v_add_f32_e32 v222, v75, v222
	v_add_f32_e32 v222, v76, v222
	v_add_f32_e32 v222, v77, v222
	v_cvt_pk_bf16_f32 v138, v72, v73
	v_cvt_pk_bf16_f32 v139, v74, v75
	ds_read_b64_tr_b16 v[68:69], v183 offset:29696
	ds_read_b64_tr_b16 v[70:71], v183 offset:30208
	v_mfma_f32_32x32x16_bf16 v[80:95], v[162:165], v[122:125], v[80:95]
	v_add_f32_e32 v222, v78, v222
	v_add_f32_e32 v222, v79, v222
	v_cvt_pk_bf16_f32 v140, v76, v77
	v_cvt_pk_bf16_f32 v141, v78, v79
	ds_read_b64_tr_b16 v[72:73], v183 offset:26624
	ds_read_b64_tr_b16 v[74:75], v183 offset:27136
	v_mfma_f32_32x32x16_bf16 v[96:111], v[158:161], v[118:121], v[96:111]
	v_cvt_pk_bf16_f32 v130, v48, v49
	v_cvt_pk_bf16_f32 v131, v50, v51
	ds_read_b64_tr_b16 v[48:49], v183 offset:30720
	ds_read_b64_tr_b16 v[50:51], v183 offset:31232
	v_mfma_f32_32x32x16_bf16 v[80:95], v[154:157], v[118:121], v[80:95]
	v_cvt_pk_bf16_f32 v132, v52, v53
	v_cvt_pk_bf16_f32 v133, v54, v55
	ds_read_b64_tr_b16 v[52:53], v183 offset:27648
	ds_read_b64_tr_b16 v[54:55], v183 offset:28160
	v_mfma_f32_32x32x16_bf16 v[96:111], v[150:153], v[114:117], v[96:111]
	v_cvt_pk_bf16_f32 v126, v56, v57
	v_cvt_pk_bf16_f32 v127, v58, v59
	ds_read_b64_tr_b16 v[56:57], v183 offset:31744
	ds_read_b64_tr_b16 v[58:59], v183 offset:32256
	v_mfma_f32_32x32x16_bf16 v[80:95], v[146:149], v[114:117], v[80:95]
	v_cvt_pk_bf16_f32 v128, v60, v61
	v_cvt_pk_bf16_f32 v129, v62, v63
	s_add_i32 m0, s24, s69
	s_nop 0
	global_load_lds_dwordx4 v188, s[2:3]
	s_add_i32 m0, s13, s70
	s_add_u32 s2, s2, 0x58000
	global_load_lds_dwordx4 v186, s[26:27]
	s_addc_u32 s3, s3, 0
	s_add_u32 s26, s26, 0x58000
	s_addc_u32 s27, s27, 0
	s_waitcnt lgkmcnt(8)
	v_mfma_f32_32x32x16_bf16 v[16:31], v[142:145], v[178:181], v[16:31]
	v_exp_f32_e32 v96, v96
	v_exp_f32_e32 v97, v97
	v_exp_f32_e32 v98, v98
	v_exp_f32_e32 v99, v99
	v_mfma_f32_32x32x16_bf16 v[0:15], v[142:145], v[174:177], v[0:15]
	v_exp_f32_e32 v100, v100
	v_exp_f32_e32 v101, v101
	v_exp_f32_e32 v102, v102
	v_exp_f32_e32 v103, v103
	v_add_u32_e32 v76, s13, v210
	ds_read_b128 v[60:63], v76
	ds_read_b128 v[174:177], v76 offset:512
	v_mfma_f32_32x32x16_bf16 v[16:31], v[138:141], v[64:67], v[16:31]
	v_exp_f32_e32 v104, v104
	v_exp_f32_e32 v105, v105
	v_exp_f32_e32 v106, v106
	v_exp_f32_e32 v107, v107
	ds_read_b128 v[178:181], v76 offset:2048
	ds_read_b128 v[170:173], v76 offset:2560
	v_mfma_f32_32x32x16_bf16 v[0:15], v[138:141], v[68:71], v[0:15]
	v_exp_f32_e32 v108, v108
	v_exp_f32_e32 v109, v109
	v_exp_f32_e32 v110, v110
	v_exp_f32_e32 v111, v111
	ds_read_b128 v[166:169], v76 offset:4096
	ds_read_b128 v[162:165], v76 offset:4608
	s_waitcnt lgkmcnt(6)
	v_mfma_f32_32x32x16_bf16 v[16:31], v[130:133], v[72:75], v[16:31]
	v_exp_f32_e32 v80, v80
	v_exp_f32_e32 v81, v81
	v_exp_f32_e32 v82, v82
	v_exp_f32_e32 v83, v83
	ds_read_b128 v[158:161], v76 offset:6144
	ds_read_b128 v[154:157], v76 offset:6656
	v_mfma_f32_32x32x16_bf16 v[0:15], v[130:133], v[48:51], v[0:15]
	v_exp_f32_e32 v84, v84
	v_exp_f32_e32 v85, v85
	v_exp_f32_e32 v86, v86
	v_exp_f32_e32 v87, v87
	v_mfma_f32_32x32x16_bf16 v[16:31], v[126:129], v[52:55], v[16:31]
	v_exp_f32_e32 v88, v88
	v_exp_f32_e32 v89, v89
	v_exp_f32_e32 v90, v90
	v_exp_f32_e32 v91, v91
	v_mfma_f32_32x32x16_bf16 v[0:15], v[126:129], v[56:59], v[0:15]
	v_exp_f32_e32 v92, v92
	v_exp_f32_e32 v93, v93
	v_exp_f32_e32 v94, v94
	v_exp_f32_e32 v95, v95
	s_add_i32 s0, s13, 0x2000
	s_cmpk_lg_i32 s13, 0x4000
	s_cselect_b32 s72, s0, 0
	s_waitcnt vmcnt(2) lgkmcnt(0)
	s_barrier
; #define WAIT_BAR(N) asm volatile("s_waitcnt vmcnt(" #N ") lgkmcnt(0)\n\ts_barrier":::"memory")
;   #define RESC() do{ if(resc){ asm volatile("s_waitcnt lgkmcnt(0)":::"memory"); \
;       _Pragma("unroll") for(int d_=0;d_<2;++d_) _Pragma("unroll") for(int r=0;r<16;++r)o[d_][r]*=wsf[crow(r,hi)]; } }while(0)
;   #define ROT() do{sl_prev=sl_cur;sl_cur=sl_next;sl_next=(sl_next==(NSLOT-1)*SLOTB)?0:sl_next+SLOTB;}while(0)
;     ...
;   int t=1;
;     ...
;   for(;t+5<NT;t+=2){
;     STEP(pB0,pB1,pA0,pA1,t,true,true,true);     WAIT_BAR(2); RESC(); ROT();
;     STEP(pA0,pA1,pB0,pB1,t+1,true,true,true);   WAIT_BAR(2); RESC(); ROT();
	v_mfma_f32_32x32x16_bf16 v[64:79], v[60:63], v[134:137], v[32:47]
	v_add_u32_e32 v196, s24, v211
	ds_read_b64_tr_b16 v[150:151], v196 offset:24576
	ds_read_b64_tr_b16 v[152:153], v196 offset:25088
	v_add_f32_e32 v222, v96, v222
	v_add_f32_e32 v222, v97, v222
	v_add_f32_e32 v222, v98, v222
	v_add_f32_e32 v222, v99, v222
	v_add_f32_e32 v222, v100, v222
	v_add_f32_e32 v222, v101, v222
	v_cvt_pk_bf16_f32 v142, v96, v97
	v_cvt_pk_bf16_f32 v143, v98, v99
	ds_read_b64_tr_b16 v[146:147], v196 offset:28672
	ds_read_b64_tr_b16 v[148:149], v196 offset:29184
	v_add_f32_e32 v222, v102, v222
	v_add_f32_e32 v222, v103, v222
	v_add_f32_e32 v222, v104, v222
	v_add_f32_e32 v222, v105, v222
	v_mfma_f32_32x32x16_bf16 v[48:63], v[174:177], v[134:137], v[32:47]
	v_cvt_pk_bf16_f32 v144, v100, v101
	v_cvt_pk_bf16_f32 v145, v102, v103
	ds_read_b64_tr_b16 v[96:97], v196 offset:25600
	ds_read_b64_tr_b16 v[98:99], v196 offset:26112
	v_mfma_f32_32x32x16_bf16 v[64:79], v[178:181], v[122:125], v[64:79]
	v_add_f32_e32 v222, v106, v222
	v_add_f32_e32 v222, v107, v222
	v_add_f32_e32 v222, v108, v222
	v_add_f32_e32 v222, v109, v222
	v_cvt_pk_bf16_f32 v138, v104, v105
	v_cvt_pk_bf16_f32 v139, v106, v107
	ds_read_b64_tr_b16 v[100:101], v196 offset:29696
	ds_read_b64_tr_b16 v[102:103], v196 offset:30208
	v_mfma_f32_32x32x16_bf16 v[48:63], v[170:173], v[122:125], v[48:63]
	v_add_f32_e32 v222, v110, v222
	v_add_f32_e32 v222, v111, v222
	v_cvt_pk_bf16_f32 v140, v108, v109
	v_cvt_pk_bf16_f32 v141, v110, v111
	ds_read_b64_tr_b16 v[104:105], v196 offset:26624
	ds_read_b64_tr_b16 v[106:107], v196 offset:27136
	v_mfma_f32_32x32x16_bf16 v[64:79], v[166:169], v[118:121], v[64:79]
	v_cvt_pk_bf16_f32 v130, v80, v81
	v_cvt_pk_bf16_f32 v131, v82, v83
	ds_read_b64_tr_b16 v[80:81], v196 offset:30720
	ds_read_b64_tr_b16 v[82:83], v196 offset:31232
	v_mfma_f32_32x32x16_bf16 v[48:63], v[162:165], v[118:121], v[48:63]
	v_cvt_pk_bf16_f32 v132, v84, v85
	v_cvt_pk_bf16_f32 v133, v86, v87
	ds_read_b64_tr_b16 v[84:85], v196 offset:27648
	ds_read_b64_tr_b16 v[86:87], v196 offset:28160
	v_mfma_f32_32x32x16_bf16 v[64:79], v[158:161], v[114:117], v[64:79]
	v_cvt_pk_bf16_f32 v126, v88, v89
	v_cvt_pk_bf16_f32 v127, v90, v91
	ds_read_b64_tr_b16 v[88:89], v196 offset:31744
	ds_read_b64_tr_b16 v[90:91], v196 offset:32256
	v_mfma_f32_32x32x16_bf16 v[48:63], v[154:157], v[114:117], v[48:63]
	v_cvt_pk_bf16_f32 v128, v92, v93
	v_cvt_pk_bf16_f32 v129, v94, v95
	s_add_i32 m0, s13, s69
	s_nop 0
	global_load_lds_dwordx4 v188, s[2:3]
	s_add_i32 m0, s72, s70
	s_add_u32 s2, s2, 0x58000
	global_load_lds_dwordx4 v186, s[26:27]
	s_addc_u32 s3, s3, 0
	s_add_u32 s26, s26, 0x58000
	s_addc_u32 s27, s27, 0
	s_waitcnt lgkmcnt(8)
	v_mfma_f32_32x32x16_bf16 v[16:31], v[142:145], v[150:153], v[16:31]
	v_exp_f32_e32 v64, v64
	v_exp_f32_e32 v65, v65
	v_exp_f32_e32 v66, v66
	v_exp_f32_e32 v67, v67
	v_mfma_f32_32x32x16_bf16 v[0:15], v[142:145], v[146:149], v[0:15]
	v_exp_f32_e32 v68, v68
	v_exp_f32_e32 v69, v69
	v_exp_f32_e32 v70, v70
	v_exp_f32_e32 v71, v71
	v_add_u32_e32 v92, s72, v210
	ds_read_b128 v[174:177], v92
	ds_read_b128 v[170:173], v92 offset:512
	v_mfma_f32_32x32x16_bf16 v[16:31], v[138:141], v[96:99], v[16:31]
	v_exp_f32_e32 v72, v72
	v_exp_f32_e32 v73, v73
	v_exp_f32_e32 v74, v74
	v_exp_f32_e32 v75, v75
	ds_read_b128 v[166:169], v92 offset:2048
	ds_read_b128 v[162:165], v92 offset:2560
	v_mfma_f32_32x32x16_bf16 v[0:15], v[138:141], v[100:103], v[0:15]
	v_exp_f32_e32 v76, v76
	v_exp_f32_e32 v77, v77
	v_exp_f32_e32 v78, v78
	v_exp_f32_e32 v79, v79
	ds_read_b128 v[158:161], v92 offset:4096
	ds_read_b128 v[154:157], v92 offset:4608
	s_waitcnt lgkmcnt(6)
	v_mfma_f32_32x32x16_bf16 v[16:31], v[130:133], v[104:107], v[16:31]
	v_exp_f32_e32 v48, v48
	v_exp_f32_e32 v49, v49
	v_exp_f32_e32 v50, v50
	v_exp_f32_e32 v51, v51
	ds_read_b128 v[150:153], v92 offset:6144
	ds_read_b128 v[146:149], v92 offset:6656
	v_mfma_f32_32x32x16_bf16 v[0:15], v[130:133], v[80:83], v[0:15]
	v_exp_f32_e32 v52, v52
	v_exp_f32_e32 v53, v53
	v_exp_f32_e32 v54, v54
	v_exp_f32_e32 v55, v55
	v_mfma_f32_32x32x16_bf16 v[16:31], v[126:129], v[84:87], v[16:31]
	v_exp_f32_e32 v56, v56
	v_exp_f32_e32 v57, v57
	v_exp_f32_e32 v58, v58
	v_exp_f32_e32 v59, v59
	v_mfma_f32_32x32x16_bf16 v[0:15], v[126:129], v[88:91], v[0:15]
	v_exp_f32_e32 v60, v60
	v_exp_f32_e32 v61, v61
	v_exp_f32_e32 v62, v62
	v_exp_f32_e32 v63, v63
	s_add_i32 s0, s72, 0x2000
	s_cmpk_lg_i32 s72, 0x4000
	s_cselect_b32 s74, s0, 0
	s_add_i32 s0, s75, 2
	s_cmp_ge_u32 s0, s71
	s_mov_b32 s75, s0
	s_mov_b32 s0, s13
	s_mov_b32 s24, s72
	s_mov_b32 s13, s74
	s_waitcnt vmcnt(2) lgkmcnt(0)
	s_barrier
	s_cbranch_scc0 .Lfb_even
	s_mov_b32 s13, s0
	s_add_i32 s75, s75, -2
	v_mov_b32_e32 v223, v222
	s_branch .LBB0_1231
.Lfb_odd:
	v_mfma_f32_32x32x16_bf16 v[96:111], v[174:177], v[134:137], v[32:47]
	v_add_u32_e32 v183, s0, v211
	ds_read_b64_tr_b16 v[178:179], v183 offset:24576
	ds_read_b64_tr_b16 v[180:181], v183 offset:25088
	v_cvt_pk_bf16_f32 v142, v64, v65
	v_cvt_pk_bf16_f32 v143, v66, v67
	ds_read_b64_tr_b16 v[174:175], v183 offset:28672
	ds_read_b64_tr_b16 v[176:177], v183 offset:29184
	v_mfma_f32_32x32x16_bf16 v[80:95], v[170:173], v[134:137], v[32:47]
	v_cvt_pk_bf16_f32 v144, v68, v69
	v_cvt_pk_bf16_f32 v145, v70, v71
	ds_read_b64_tr_b16 v[64:65], v183 offset:25600
	ds_read_b64_tr_b16 v[66:67], v183 offset:26112
	v_mfma_f32_32x32x16_bf16 v[96:111], v[166:169], v[122:125], v[96:111]
	v_cvt_pk_bf16_f32 v138, v72, v73
	v_cvt_pk_bf16_f32 v139, v74, v75
	ds_read_b64_tr_b16 v[68:69], v183 offset:29696
	ds_read_b64_tr_b16 v[70:71], v183 offset:30208
	v_mfma_f32_32x32x16_bf16 v[80:95], v[162:165], v[122:125], v[80:95]
	v_add_f32_e32 v222, v48, v222
	v_add_f32_e32 v222, v49, v222
	v_cvt_pk_bf16_f32 v140, v76, v77
	v_cvt_pk_bf16_f32 v141, v78, v79
	ds_read_b64_tr_b16 v[72:73], v183 offset:26624
	ds_read_b64_tr_b16 v[74:75], v183 offset:27136
	v_mfma_f32_32x32x16_bf16 v[96:111], v[158:161], v[118:121], v[96:111]
	v_add_f32_e32 v222, v50, v222
	v_add_f32_e32 v222, v51, v222
	v_add_f32_e32 v222, v52, v222
	v_add_f32_e32 v222, v53, v222
	v_cvt_pk_bf16_f32 v130, v48, v49
	v_cvt_pk_bf16_f32 v131, v50, v51
	ds_read_b64_tr_b16 v[48:49], v183 offset:30720
	ds_read_b64_tr_b16 v[50:51], v183 offset:31232
	v_mfma_f32_32x32x16_bf16 v[80:95], v[154:157], v[118:121], v[80:95]
	v_add_f32_e32 v222, v54, v222
	v_add_f32_e32 v222, v55, v222
	v_add_f32_e32 v222, v56, v222
	v_add_f32_e32 v222, v57, v222
	v_cvt_pk_bf16_f32 v132, v52, v53
	v_cvt_pk_bf16_f32 v133, v54, v55
	ds_read_b64_tr_b16 v[52:53], v183 offset:27648
	ds_read_b64_tr_b16 v[54:55], v183 offset:28160
	v_mfma_f32_32x32x16_bf16 v[96:111], v[150:153], v[114:117], v[96:111]
	v_add_f32_e32 v222, v58, v222
	v_add_f32_e32 v222, v59, v222
	v_add_f32_e32 v222, v60, v222
	v_add_f32_e32 v222, v61, v222
	v_cvt_pk_bf16_f32 v126, v56, v57
	v_cvt_pk_bf16_f32 v127, v58, v59
	ds_read_b64_tr_b16 v[56:57], v183 offset:31744
	ds_read_b64_tr_b16 v[58:59], v183 offset:32256
	v_mfma_f32_32x32x16_bf16 v[80:95], v[146:149], v[114:117], v[80:95]
	v_add_f32_e32 v222, v62, v222
	v_add_f32_e32 v222, v63, v222
	v_cvt_pk_bf16_f32 v128, v60, v61
	v_cvt_pk_bf16_f32 v129, v62, v63
	s_add_i32 m0, s24, s69
	s_nop 0
	global_load_lds_dwordx4 v188, s[2:3]
	s_add_i32 m0, s13, s70
	s_add_u32 s2, s2, 0x58000
	global_load_lds_dwordx4 v186, s[26:27]
	s_addc_u32 s3, s3, 0
	s_add_u32 s26, s26, 0x58000
	s_addc_u32 s27, s27, 0
	s_waitcnt lgkmcnt(8)
	v_mfma_f32_32x32x16_bf16 v[16:31], v[142:145], v[178:181], v[16:31]
	v_exp_f32_e32 v96, v96
	v_exp_f32_e32 v97, v97
	v_exp_f32_e32 v98, v98
	v_exp_f32_e32 v99, v99
	v_mfma_f32_32x32x16_bf16 v[0:15], v[142:145], v[174:177], v[0:15]
	v_exp_f32_e32 v100, v100
	v_exp_f32_e32 v101, v101
	v_exp_f32_e32 v102, v102
	v_exp_f32_e32 v103, v103
	v_add_u32_e32 v76, s13, v210
	ds_read_b128 v[60:63], v76
	ds_read_b128 v[174:177], v76 offset:512
	v_mfma_f32_32x32x16_bf16 v[16:31], v[138:141], v[64:67], v[16:31]
	v_exp_f32_e32 v104, v104
	v_exp_f32_e32 v105, v105
	v_exp_f32_e32 v106, v106
	v_exp_f32_e32 v107, v107
	ds_read_b128 v[178:181], v76 offset:2048
	ds_read_b128 v[170:173], v76 offset:2560
	v_mfma_f32_32x32x16_bf16 v[0:15], v[138:141], v[68:71], v[0:15]
	v_exp_f32_e32 v108, v108
	v_exp_f32_e32 v109, v109
	v_exp_f32_e32 v110, v110
	v_exp_f32_e32 v111, v111
	ds_read_b128 v[166:169], v76 offset:4096
	ds_read_b128 v[162:165], v76 offset:4608
	s_waitcnt lgkmcnt(6)
	v_mfma_f32_32x32x16_bf16 v[16:31], v[130:133], v[72:75], v[16:31]
	v_exp_f32_e32 v80, v80
	v_exp_f32_e32 v81, v81
	v_exp_f32_e32 v82, v82
	v_exp_f32_e32 v83, v83
	ds_read_b128 v[158:161], v76 offset:6144
	ds_read_b128 v[154:157], v76 offset:6656
	v_mfma_f32_32x32x16_bf16 v[0:15], v[130:133], v[48:51], v[0:15]
	v_exp_f32_e32 v84, v84
	v_exp_f32_e32 v85, v85
	v_exp_f32_e32 v86, v86
	v_exp_f32_e32 v87, v87
	v_mfma_f32_32x32x16_bf16 v[16:31], v[126:129], v[52:55], v[16:31]
	v_exp_f32_e32 v88, v88
	v_exp_f32_e32 v89, v89
	v_exp_f32_e32 v90, v90
	v_exp_f32_e32 v91, v91
	v_mfma_f32_32x32x16_bf16 v[0:15], v[126:129], v[56:59], v[0:15]
	v_exp_f32_e32 v92, v92
	v_exp_f32_e32 v93, v93
	v_exp_f32_e32 v94, v94
	v_exp_f32_e32 v95, v95
	s_add_i32 s0, s13, 0x2000
	s_cmpk_lg_i32 s13, 0x4000
	s_cselect_b32 s72, s0, 0
	s_waitcnt vmcnt(2) lgkmcnt(0)
	s_barrier
; #define WAIT_BAR(N) asm volatile("s_waitcnt vmcnt(" #N ") lgkmcnt(0)\n\ts_barrier":::"memory")
;   #define RESC() do{ if(resc){ asm volatile("s_waitcnt lgkmcnt(0)":::"memory"); \
;       _Pragma("unroll") for(int d_=0;d_<2;++d_) _Pragma("unroll") for(int r=0;r<16;++r)o[d_][r]*=wsf[crow(r,hi)]; } }while(0)
;   #define ROT() do{sl_prev=sl_cur;sl_cur=sl_next;sl_next=(sl_next==(NSLOT-1)*SLOTB)?0:sl_next+SLOTB;}while(0)
;     ...
;   int t=1;
;     ...
;   for(;t+5<NT;t+=2){
;     STEP(pB0,pB1,pA0,pA1,t,true,true,true);     WAIT_BAR(2); RESC(); ROT();
;     STEP(pA0,pA1,pB0,pB1,t+1,true,true,true);   WAIT_BAR(2); RESC(); ROT();
	v_mfma_f32_32x32x16_bf16 v[64:79], v[60:63], v[134:137], v[32:47]
	v_add_u32_e32 v196, s24, v211
	ds_read_b64_tr_b16 v[150:151], v196 offset:24576
	ds_read_b64_tr_b16 v[152:153], v196 offset:25088
	v_cvt_pk_bf16_f32 v142, v96, v97
	v_cvt_pk_bf16_f32 v143, v98, v99
	ds_read_b64_tr_b16 v[146:147], v196 offset:28672
	ds_read_b64_tr_b16 v[148:149], v196 offset:29184
	v_mfma_f32_32x32x16_bf16 v[48:63], v[174:177], v[134:137], v[32:47]
	v_cvt_pk_bf16_f32 v144, v100, v101
	v_cvt_pk_bf16_f32 v145, v102, v103
	ds_read_b64_tr_b16 v[96:97], v196 offset:25600
	ds_read_b64_tr_b16 v[98:99], v196 offset:26112
	v_mfma_f32_32x32x16_bf16 v[64:79], v[178:181], v[122:125], v[64:79]
	v_cvt_pk_bf16_f32 v138, v104, v105
	v_cvt_pk_bf16_f32 v139, v106, v107
	ds_read_b64_tr_b16 v[100:101], v196 offset:29696
	ds_read_b64_tr_b16 v[102:103], v196 offset:30208
	v_mfma_f32_32x32x16_bf16 v[48:63], v[170:173], v[122:125], v[48:63]
	v_add_f32_e32 v222, v80, v222
	v_add_f32_e32 v222, v81, v222
	v_cvt_pk_bf16_f32 v140, v108, v109
	v_cvt_pk_bf16_f32 v141, v110, v111
	ds_read_b64_tr_b16 v[104:105], v196 offset:26624
	ds_read_b64_tr_b16 v[106:107], v196 offset:27136
	v_mfma_f32_32x32x16_bf16 v[64:79], v[166:169], v[118:121], v[64:79]
	v_add_f32_e32 v222, v82, v222
	v_add_f32_e32 v222, v83, v222
	v_add_f32_e32 v222, v84, v222
	v_add_f32_e32 v222, v85, v222
	v_cvt_pk_bf16_f32 v130, v80, v81
	v_cvt_pk_bf16_f32 v131, v82, v83
	ds_read_b64_tr_b16 v[80:81], v196 offset:30720
	ds_read_b64_tr_b16 v[82:83], v196 offset:31232
	v_mfma_f32_32x32x16_bf16 v[48:63], v[162:165], v[118:121], v[48:63]
	v_add_f32_e32 v222, v86, v222
	v_add_f32_e32 v222, v87, v222
	v_add_f32_e32 v222, v88, v222
	v_add_f32_e32 v222, v89, v222
	v_cvt_pk_bf16_f32 v132, v84, v85
	v_cvt_pk_bf16_f32 v133, v86, v87
	ds_read_b64_tr_b16 v[84:85], v196 offset:27648
	ds_read_b64_tr_b16 v[86:87], v196 offset:28160
	v_mfma_f32_32x32x16_bf16 v[64:79], v[158:161], v[114:117], v[64:79]
	v_add_f32_e32 v222, v90, v222
	v_add_f32_e32 v222, v91, v222
	v_add_f32_e32 v222, v92, v222
	v_add_f32_e32 v222, v93, v222
	v_cvt_pk_bf16_f32 v126, v88, v89
	v_cvt_pk_bf16_f32 v127, v90, v91
	ds_read_b64_tr_b16 v[88:89], v196 offset:31744
	ds_read_b64_tr_b16 v[90:91], v196 offset:32256
	v_mfma_f32_32x32x16_bf16 v[48:63], v[154:157], v[114:117], v[48:63]
	v_add_f32_e32 v222, v94, v222
	v_add_f32_e32 v222, v95, v222
	v_cvt_pk_bf16_f32 v128, v92, v93
	v_cvt_pk_bf16_f32 v129, v94, v95
	s_add_i32 m0, s13, s69
	s_nop 0
	global_load_lds_dwordx4 v188, s[2:3]
	s_add_i32 m0, s72, s70
	s_add_u32 s2, s2, 0x58000
	global_load_lds_dwordx4 v186, s[26:27]
	s_addc_u32 s3, s3, 0
	s_add_u32 s26, s26, 0x58000
	s_addc_u32 s27, s27, 0
	s_waitcnt lgkmcnt(8)
	v_mfma_f32_32x32x16_bf16 v[16:31], v[142:145], v[150:153], v[16:31]
	v_exp_f32_e32 v64, v64
	v_exp_f32_e32 v65, v65
	v_exp_f32_e32 v66, v66
	v_exp_f32_e32 v67, v67
	v_mfma_f32_32x32x16_bf16 v[0:15], v[142:145], v[146:149], v[0:15]
	v_exp_f32_e32 v68, v68
	v_exp_f32_e32 v69, v69
	v_exp_f32_e32 v70, v70
	v_exp_f32_e32 v71, v71
	v_add_u32_e32 v92, s72, v210
	ds_read_b128 v[174:177], v92
	ds_read_b128 v[170:173], v92 offset:512
	v_mfma_f32_32x32x16_bf16 v[16:31], v[138:141], v[96:99], v[16:31]
	v_exp_f32_e32 v72, v72
	v_exp_f32_e32 v73, v73
	v_exp_f32_e32 v74, v74
	v_exp_f32_e32 v75, v75
	ds_read_b128 v[166:169], v92 offset:2048
	ds_read_b128 v[162:165], v92 offset:2560
	v_mfma_f32_32x32x16_bf16 v[0:15], v[138:141], v[100:103], v[0:15]
	v_exp_f32_e32 v76, v76
	v_exp_f32_e32 v77, v77
	v_exp_f32_e32 v78, v78
	v_exp_f32_e32 v79, v79
	ds_read_b128 v[158:161], v92 offset:4096
	ds_read_b128 v[154:157], v92 offset:4608
	s_waitcnt lgkmcnt(6)
	v_mfma_f32_32x32x16_bf16 v[16:31], v[130:133], v[104:107], v[16:31]
	v_exp_f32_e32 v48, v48
	v_exp_f32_e32 v49, v49
	v_exp_f32_e32 v50, v50
	v_exp_f32_e32 v51, v51
	ds_read_b128 v[150:153], v92 offset:6144
	ds_read_b128 v[146:149], v92 offset:6656
	v_mfma_f32_32x32x16_bf16 v[0:15], v[130:133], v[80:83], v[0:15]
	v_exp_f32_e32 v52, v52
	v_exp_f32_e32 v53, v53
	v_exp_f32_e32 v54, v54
	v_exp_f32_e32 v55, v55
	v_mfma_f32_32x32x16_bf16 v[16:31], v[126:129], v[84:87], v[16:31]
	v_exp_f32_e32 v56, v56
	v_exp_f32_e32 v57, v57
	v_exp_f32_e32 v58, v58
	v_exp_f32_e32 v59, v59
	v_mfma_f32_32x32x16_bf16 v[0:15], v[126:129], v[88:91], v[0:15]
	v_exp_f32_e32 v60, v60
	v_exp_f32_e32 v61, v61
	v_exp_f32_e32 v62, v62
	v_exp_f32_e32 v63, v63
	s_add_i32 s0, s72, 0x2000
	s_cmpk_lg_i32 s72, 0x4000
	s_cselect_b32 s74, s0, 0
	s_add_i32 s0, s75, 2
	s_cmp_ge_u32 s0, s71
	s_mov_b32 s75, s0
	s_mov_b32 s0, s13
	s_mov_b32 s24, s72
	s_mov_b32 s13, s74
	s_waitcnt vmcnt(2) lgkmcnt(0)
	s_barrier
	s_cbranch_scc0 .Lfb_odd
	s_mov_b32 s13, s0
	s_add_i32 s75, s75, -2
	v_mov_b32_e32 v223, v222
	s_branch .LBB0_1231

; __device__ __forceinline__ int crow(int r,int hi){return (r&3)+8*(r>>2)+4*hi;}
; #define SBAR() __builtin_amdgcn_sched_barrier(0)
;   #define RESC() do{ if(resc){ asm volatile("s_waitcnt lgkmcnt(0)":::"memory"); \
;       _Pragma("unroll") for(int d_=0;d_<2;++d_) _Pragma("unroll") for(int r=0;r<16;++r)o[d_][r]*=wsf[crow(r,hi)]; } }while(0)
;   #define PKW(P,B) cvtpk_s(P[B],P[B+1])
;     ...
;   STEP(pB0,pB1,pA0,pA1,NT-1,false,false,false); RESC();
;   { float sacc=pB0[0]+pB0[1]; _Pragma("unroll") for(int r=2;r<16;++r)sacc+=pB0[r]; _Pragma("unroll") for(int r=0;r<16;++r)sacc+=pB1[r]; l_reg+=sacc;
;     pw0=(u32x4){PKW(pB0,0),PKW(pB0,2),PKW(pB0,4),PKW(pB0,6)};pw1=(u32x4){PKW(pB0,8),PKW(pB0,10),PKW(pB0,12),PKW(pB0,14)};pw2=(u32x4){PKW(pB1,0),PKW(pB1,2),PKW(pB1,4),PKW(pB1,6)};pw3=(u32x4){PKW(pB1,8),PKW(pB1,10),PKW(pB1,12),PKW(pB1,14)};
;     SBAR(); pv(o,vb0+sl_cur,PAF(0),PAF(1),PAF(2),PAF(3)); }
;     ...
;   {auto rr=__builtin_amdgcn_permlane32_swap(__float_as_uint(l_reg),__float_as_uint(l_reg),false,false);l_reg=__uint_as_float(rr[0])+__uint_as_float(rr[1]);}
;   if(MODE==2)l_reg+=__builtin_amdgcn_exp2f(sinkl2-mhat);
;   if(MODE==3){ const int p_=wid*QBLK+r32; if(hi==0&&p_<len)stat[p_]=mhat+__builtin_amdgcn_logf(l_reg); }
;   if(hi==0)wsf[32+r32]=l_reg;asm volatile("s_waitcnt lgkmcnt(0)":::"memory");
;   float rli[16];
;   #pragma unroll
;   for(int r=0;r<16;++r)rli[r]=__builtin_amdgcn_rcpf(wsf[32+crow(r,hi)]);
.LBB0_1229:
	v_add_f32_e32 v65, v48, v49
	v_add_f32_e32 v65, v50, v65
	v_add_f32_e32 v65, v51, v65
	v_add_f32_e32 v65, v52, v65
	v_add_f32_e32 v65, v53, v65
	v_add_f32_e32 v65, v54, v65
	v_add_f32_e32 v65, v55, v65
	v_add_f32_e32 v65, v56, v65
	v_add_f32_e32 v65, v57, v65
	v_add_f32_e32 v65, v58, v65
	v_add_f32_e32 v65, v59, v65
	v_add_f32_e32 v65, v60, v65
	v_add_f32_e32 v65, v61, v65
	v_add_f32_e32 v65, v62, v65
	v_add_f32_e32 v65, v63, v65
	v_add_f32_e32 v65, v32, v65
	v_add_f32_e32 v65, v33, v65
	v_add_f32_e32 v65, v34, v65
	v_add_f32_e32 v65, v35, v65
	v_add_f32_e32 v65, v36, v65
	v_add_f32_e32 v65, v37, v65
	v_add_f32_e32 v65, v38, v65
	v_add_f32_e32 v65, v39, v65
	v_add_f32_e32 v65, v40, v65
	v_add_f32_e32 v65, v41, v65
	v_add_f32_e32 v65, v42, v65
	v_add_f32_e32 v65, v43, v65
	v_add_f32_e32 v65, v44, v65
	v_add_f32_e32 v65, v45, v65
	s_cmp_lg_u32 0, -1
	v_add_f32_e32 v65, v46, v65
	s_cselect_b32 s0, 0, 0
	v_add_f32_e32 v65, v47, v65
	s_addk_i32 s0, 0x6000
	v_add_f32_e32 v65, v80, v65
	v_cvt_pk_bf16_f32 v32, v32, v33
	v_add3_u32 v66, v206, s0, v204
	v_cvt_pk_bf16_f32 v48, v48, v49
	v_cvt_pk_bf16_f32 v49, v50, v51
	v_cvt_pk_bf16_f32 v50, v52, v53
	v_cvt_pk_bf16_f32 v51, v54, v55
	v_cvt_pk_bf16_f32 v52, v56, v57
	v_cvt_pk_bf16_f32 v53, v58, v59
	v_cvt_pk_bf16_f32 v54, v60, v61
	v_cvt_pk_bf16_f32 v55, v62, v63
	v_cvt_pk_bf16_f32 v33, v34, v35
	v_cvt_pk_bf16_f32 v34, v36, v37
	v_cvt_pk_bf16_f32 v35, v38, v39
	v_cvt_pk_bf16_f32 v36, v40, v41
	v_cvt_pk_bf16_f32 v37, v42, v43
	v_cvt_pk_bf16_f32 v38, v44, v45
	v_cvt_pk_bf16_f32 v39, v46, v47
	v_add3_u32 v66, v66, v191, s72
	ds_read_b64_tr_b16 v[40:41],v66 offset:0
	ds_read_b64_tr_b16 v[42:43],v66 offset:512
	ds_read_b64_tr_b16 v[44:45],v66 offset:1024
	ds_read_b64_tr_b16 v[46:47],v66 offset:1536
	ds_read_b64_tr_b16 v[56:57],v66 offset:2048
	ds_read_b64_tr_b16 v[58:59],v66 offset:2560
	ds_read_b64_tr_b16 v[60:61],v66 offset:3072
	ds_read_b64_tr_b16 v[62:63],v66 offset:3584
	s_waitcnt lgkmcnt(0)
	s_nop 0
	v_mfma_f32_32x32x16_bf16 v[16:31], v[48:51], v[40:43], v[16:31]
	ds_read_b64_tr_b16 v[40:41],v66 offset:4096
	ds_read_b64_tr_b16 v[42:43],v66 offset:4608
	v_mfma_f32_32x32x16_bf16 v[16:31], v[52:55], v[44:47], v[16:31]
	ds_read_b64_tr_b16 v[44:45],v66 offset:5120
	ds_read_b64_tr_b16 v[46:47],v66 offset:5632
	v_mfma_f32_32x32x16_bf16 v[16:31], v[32:35], v[56:59], v[16:31]
	ds_read_b64_tr_b16 v[56:57],v66 offset:6144
	ds_read_b64_tr_b16 v[58:59],v66 offset:6656
	v_mfma_f32_32x32x16_bf16 v[16:31], v[36:39], v[60:63], v[16:31]
	ds_read_b64_tr_b16 v[60:61],v66 offset:7168
	ds_read_b64_tr_b16 v[62:63],v66 offset:7680
	s_waitcnt lgkmcnt(0)
	v_mfma_f32_32x32x16_bf16 v[0:15], v[48:51], v[40:43], v[0:15]
	v_cmp_gt_u32_e32 vcc, 32, v200
	v_mfma_f32_32x32x16_bf16 v[0:15], v[52:55], v[44:47], v[0:15]
	v_mfma_f32_32x32x16_bf16 v[0:15], v[32:35], v[56:59], v[0:15]
	v_mov_b32_e32 v32, v65
	s_nop 1
	v_permlane32_swap_b32_e32 v65, v32
	v_mfma_f32_32x32x16_bf16 v[0:15], v[36:39], v[60:63], v[0:15]
	s_mov_b32 s82, 0x41000000
	s_bitcmp1_b32 s32, 0
	s_cbranch_scc0 .Lue_a
	v_and_b32_e32 v224, 31, v230
	v_lshrrev_b32_e32 v225, 6, v230
	v_lshl_or_b32 v224, v225, 5, v224
	s_bfe_u32 s2, s32, 0x60010
	s_sub_i32 s2, 63, s2
	s_lshl_b32 s2, s2, 8
	v_add_u32_e32 v224, s2, v224
	s_bfe_u32 s3, s32, 0x30009
	v_lshlrev_b32_e32 v226, 5, v224
	s_lshl_b32 s2, s3, 2
	s_add_i32 s2, s2, 0xf600000
	v_add_u32_e32 v226, s2, v226
	s_bitcmp1_b32 s32, 8
	s_cbranch_scc0 .Lue_a
	v_bfe_u32 v225, v230, 5, 1
	v_lshlrev_b32_e32 v227, 6, v224
	v_lshl_add_u32 v227, v225, 2, v227
	s_lshl_b32 s2, s3, 3
	s_add_i32 s2, s2, 0xf700000
	v_add_u32_e32 v227, s2, v227
	global_store_dword v227, v223, s[16:17]
.Lue_a:
	s_and_saveexec_b64 s[0:1], vcc
	s_cbranch_execz .LBB0_1074
	v_add_f32_e32 v32, v65, v32
	s_bitcmp1_b32 s32, 0
	s_cbranch_scc0 .Lue_b
	s_bitcmp1_b32 s32, 8
	s_cbranch_scc1 .Lue_c
	global_store_dword v226, v32, s[16:17]
	s_nop 1
.Lue_c:
	v_mov_b32_e32 v32, 1.0
.Lue_b:
	ds_write_b32 v207, v32 offset:49280
	s_branch .LBB0_1074

; __device__ __forceinline__ int opaque_tid() { int t = threadIdx.x; asm volatile("" : "+v"(t)); return t; }
; #define ARGS() (*opaque_kargs())
; #define WSPTR() ({ unsigned char* w_ = ARGS().ws; asm volatile("" : "+s"(w_)); w_; })
; #define G opaque_s(G0)
; #define bx opaque_s(bx0)
; __global__ void __launch_bounds__(NWAVES * 64, 2) mega_fwd(Args args_) {
;     ...
;             { unsigned char* ws = WSPTR(); const int l = step / 3;
;               const int tid = opaque_tid(), lane = tid & 63, wave = __builtin_amdgcn_readfirstlane(tid >> 6);
;               const int gw = bx * NWAVES + wave, NGW = G * NWAVES;
;               const bf16* OB = (const bf16*)(ws + WS_OB); bf16* OC = (bf16*)(ws + WS_OCN);
;               const float lam_init = l == 0 ? 0.2f : 0.35550907f;
;               const float s1 = wave_sum(ARGS().in[14][l * 64 + lane] * ARGS().in[15][l * 64 + lane]), s2 = wave_sum(ARGS().in[16][l * 64 + lane] * ARGS().in[17][l * 64 + lane]);
;               const float lam = expf(s1) - expf(s2) + lam_init;
;               const int h = lane >> 4, c0 = (lane & 15) * 8;
;               f32x4 sg0 = *(const f32x4*)(ARGS().in[18] + l * 128 + c0), sg1 = *(const f32x4*)(ARGS().in[18] + l * 128 + c0 + 4);
;               sg0 = sg0 * (1.0f - lam_init); sg1 = sg1 * (1.0f - lam_init);
.LBB0_1361:
	s_mov_b64 s[0:1], s[84:85]
	s_load_dwordx2 s[4:5], s[0:1], 0xe0
	v_mov_b32_e32 v8, v230
	s_mov_b32 s0, s76
	s_mov_b32 s1, s86
	s_mov_b64 s[2:3], s[84:85]
	s_waitcnt lgkmcnt(0)
	s_load_dwordx2 s[2:3], s[2:3], 0x70
	v_and_b32_e32 v9, 63, v8
	v_readlane_b32 s6, v254, 45
	s_lshl_b32 s0, s0, 3
	v_and_b32_e32 v11, 64, v236
	v_or_b32_e32 v0, s6, v9
	v_lshlrev_b32_e32 v0, 2, v0
	s_waitcnt lgkmcnt(0)
	global_load_dword v5, v0, s[2:3]
	s_mov_b64 s[2:3], s[84:85]
	s_load_dwordx2 s[2:3], s[2:3], 0x78
	s_mov_b64 s[6:7], s[84:85]
	v_xor_b32_e32 v12, 1, v236
	v_add_u32_e32 v11, 64, v11
	v_cmp_lt_i32_e32 vcc, v12, v11
	s_waitcnt lgkmcnt(0)
	global_load_dword v6, v0, s[2:3]
	s_mov_b64 s[2:3], s[84:85]
	s_load_dwordx2 s[2:3], s[2:3], 0x80
	v_cndmask_b32_e32 v12, v236, v12, vcc
	v_lshlrev_b32_e32 v24, 2, v12
	v_xor_b32_e32 v13, 2, v236
	v_cmp_lt_i32_e32 vcc, v13, v11
	s_waitcnt lgkmcnt(0)
	global_load_dword v7, v0, s[2:3]
	s_load_dwordx2 s[2:3], s[6:7], 0x88
	v_readfirstlane_b32 s6, v8
	s_ashr_i32 s6, s6, 6
	s_add_i32 s0, s0, s6
	v_readlane_b32 s6, v254, 15
	s_waitcnt lgkmcnt(0)
	global_load_dword v10, v0, s[2:3]
	s_mov_b64 s[2:3], s[84:85]
	s_load_dwordx2 s[2:3], s[2:3], 0x90
	v_readlane_b32 s7, v254, 16
	s_and_b64 s[6:7], s[6:7], exec
	s_cselect_b32 s6, 0x80, 0
	v_lshlrev_b32_e32 v0, 3, v8
	s_lshl_b32 s6, s6, 2
	v_and_b32_e32 v0, 0x78, v0
	s_waitcnt lgkmcnt(0)
	s_add_u32 s2, s2, s6
	v_lshlrev_b32_e32 v4, 2, v0
	s_addc_u32 s3, s3, 0
	global_load_dwordx4 v[0:3], v4, s[2:3]
	v_cndmask_b32_e32 v13, v236, v13, vcc
	v_lshlrev_b32_e32 v25, 2, v13
	v_xor_b32_e32 v14, 4, v236
	v_cmp_lt_i32_e32 vcc, v14, v11
	s_mov_b64 s[2:3], s[84:85]
	s_cmpk_gt_i32 s0, 0x3fff
	v_cndmask_b32_e32 v13, v236, v14, vcc
	v_lshlrev_b32_e32 v26, 2, v13
	s_waitcnt vmcnt(0)
	v_mul_f32_e32 v12, v5, v6
	ds_bpermute_b32 v12, v24, v12
	s_waitcnt lgkmcnt(0)
	v_fmac_f32_e32 v12, v5, v6
	ds_bpermute_b32 v5, v25, v12
	v_xor_b32_e32 v6, 8, v236
	v_cmp_lt_i32_e32 vcc, v6, v11
	s_waitcnt lgkmcnt(0)
	v_add_f32_e32 v5, v12, v5
	ds_bpermute_b32 v13, v26, v5
	v_cndmask_b32_e32 v6, v236, v6, vcc
	v_mul_f32_e32 v12, v7, v10
	ds_bpermute_b32 v12, v24, v12
	v_lshlrev_b32_e32 v27, 2, v6
	s_waitcnt lgkmcnt(1)
	v_add_f32_e32 v5, v5, v13
	ds_bpermute_b32 v6, v27, v5
	s_waitcnt lgkmcnt(1)
	v_fmac_f32_e32 v12, v7, v10
	ds_bpermute_b32 v7, v25, v12
	v_xor_b32_e32 v10, 16, v236
	s_waitcnt lgkmcnt(1)
	v_add_f32_e32 v5, v5, v6
	v_cmp_lt_i32_e32 vcc, v10, v11
	s_waitcnt lgkmcnt(0)
	v_add_f32_e32 v6, v12, v7
	ds_bpermute_b32 v7, v26, v6
	v_cndmask_b32_e32 v10, v236, v10, vcc
	v_lshlrev_b32_e32 v143, 2, v10
	ds_bpermute_b32 v10, v143, v5
	s_waitcnt lgkmcnt(1)
	v_add_f32_e32 v6, v6, v7
	ds_bpermute_b32 v7, v27, v6
	s_waitcnt lgkmcnt(1)
	v_add_f32_e32 v12, v5, v10
	v_xor_b32_e32 v5, 32, v236
	v_cmp_lt_i32_e32 vcc, v5, v11
	s_waitcnt lgkmcnt(0)
	v_add_f32_e32 v6, v6, v7
	ds_bpermute_b32 v7, v143, v6
	v_cndmask_b32_e32 v5, v236, v5, vcc
	v_lshlrev_b32_e32 v142, 2, v5
	ds_bpermute_b32 v13, v142, v12
	s_waitcnt lgkmcnt(1)
	v_add_f32_e32 v10, v6, v7
	ds_bpermute_b32 v11, v142, v10
	s_cbranch_scc1 .LBB0_1364
	s_load_dwordx2 s[8:9], s[2:3], 0x90
	s_lshl_b32 s2, s1, 3
	v_mov_b32_e32 v14, 0x3eb60549
	v_mov_b32_e32 v15, 0x3e4ccccd
	s_waitcnt lgkmcnt(0)
	v_add_f32_e32 v19, v12, v13
	s_add_u32 s6, s8, s6
	s_addc_u32 s7, s9, 0
	global_load_dwordx4 v[4:7], v4, s[6:7] offset:16
	v_readlane_b32 s6, v254, 35
	v_readlane_b32 s7, v254, 36
	v_add_f32_e32 v10, v10, v11
	v_lshlrev_b32_e32 v9, 4, v9
	v_cndmask_b32_e64 v18, v14, v15, s[6:7]
	s_mul_i32 s6, s1, 0x6000
	v_mul_f32_e32 v14, 0x3fb8aa3b, v19
	s_mov_b32 s1, 0x3fb8aa3b
	v_mul_f32_e32 v15, 0x3fb8aa3b, v10
	v_fma_f32 v16, v19, s1, -v14
	v_rndne_f32_e32 v17, v14
	v_fma_f32 v20, v10, s1, -v15
	v_rndne_f32_e32 v21, v15
	v_fmac_f32_e32 v16, 0x32a5705f, v19
	v_sub_f32_e32 v14, v14, v17
	v_and_b32_e32 v12, 48, v8
	v_fmac_f32_e32 v20, 0x32a5705f, v10
	v_sub_f32_e32 v15, v15, v21
	v_add_f32_e32 v14, v14, v16
	v_lshlrev_b32_e32 v11, 4, v8
	v_sub_f32_e32 v8, 1.0, v18
	v_and_b32_e32 v9, 0x300, v9
	v_lshlrev_b32_e32 v112, 5, v12
	v_cvt_i32_f32_e32 v17, v17
	v_add_f32_e32 v15, v15, v20
	v_exp_f32_e32 v16, v14
	v_and_b32_e32 v11, 0xf0, v11
	v_pk_mul_f32 v[12:13], v[8:9], v[2:3] op_sel_hi:[0,1]
	v_mad_i64_i32 v[2:3], s[12:13], s0, v241, v[112:113]
	v_cvt_i32_f32_e32 v21, v21
	v_exp_f32_e32 v20, v15
	v_or_b32_e32 v2, v2, v11
	s_ashr_i32 s1, s0, 31
	s_mov_b64 s[8:9], 0xb400500
	v_lshl_add_u64 v[2:3], s[4:5], 0, v[2:3]
	s_lshl_b64 s[12:13], s[0:1], 10
	s_mov_b32 s1, 0xc2ce8ed0
	v_pk_mul_f32 v[0:1], v[8:9], v[0:1] op_sel_hi:[0,1]
	v_lshl_add_u64 v[14:15], v[2:3], 0, s[8:9]
	v_or3_b32 v2, s12, v9, v11
	v_mov_b32_e32 v3, s13
	v_ldexp_f32 v9, v16, v17
	v_cmp_ngt_f32_e32 vcc, s1, v19
	s_mov_b64 s[10:11], 0x9c00000
	v_ldexp_f32 v11, v20, v21
	v_lshl_add_u64 v[2:3], s[4:5], 0, v[2:3]
	v_cndmask_b32_e32 v9, 0, v9, vcc
	v_cmp_ngt_f32_e32 vcc, s1, v10
	s_mov_b32 s1, 0x42b17218
	v_lshl_add_u64 v[16:17], v[2:3], 0, s[10:11]
	v_cndmask_b32_e32 v11, 0, v11, vcc
	v_cmp_nlt_f32_e32 vcc, s1, v19
	v_mov_b32_e32 v3, 0x7f800000
	s_ashr_i32 s3, s2, 31
	v_cndmask_b32_e32 v2, v3, v9, vcc
	v_cmp_nlt_f32_e32 vcc, s1, v10
	s_lshl_b64 s[8:9], s[2:3], 10
	s_mul_hi_i32 s7, s2, 0xc00
	v_cndmask_b32_e32 v3, v3, v11, vcc
	v_sub_f32_e32 v2, v2, v3
	v_add_f32_e32 v18, v18, v2
	v_mov_b32_e32 v19, v18
	v_mov_b32_e32 v2, v18
	v_mov_b32_e32 v3, v18
	s_waitcnt vmcnt(0)
	v_pk_mul_f32 v[20:21], v[8:9], v[4:5] op_sel_hi:[0,1]
	v_pk_mul_f32 v[22:23], v[8:9], v[6:7] op_sel_hi:[0,1]
	v_mbcnt_lo_u32_b32 v38, -1, 0
	v_mbcnt_hi_u32_b32 v38, -1, v38
	v_lshrrev_b32_e32 v38, 4, v38
	s_lshl_b32 s24, s0, 5
	s_add_i32 s24, s24, 0xf600000
	s_lshl_b32 s25, s0, 6
	s_add_i32 s25, s25, 0xf700000
	v_lshl_add_u32 v39, v38, 4, s25
	v_lshl_add_u32 v38, v38, 3, s24
	s_lshl_b32 s12, s2, 5
	s_lshl_b32 s13, s2, 6
	s_bitcmp1_b32 s32, 0
	s_cselect_b64 s[14:15], -1, 0
; __device__ __forceinline__ u32x4 pack8(const f32x4 a, const f32x4 b) { u32x4 w; w.x = cvt_pk_bf16(a[0], a[1]); w.y = cvt_pk_bf16(a[2], a[3]); w.z = cvt_pk_bf16(b[0], b[1]); w.w = cvt_pk_bf16(b[2], b[3]); return w; }
; __global__ void __launch_bounds__(NWAVES * 64, 2) mega_fwd(Args args_) {
;     ...
;               for (int m = gw; m < M; m += NGW) {
;                   const bf16* op = OB + (size_t)m * OPW + 512 + 256 * h + c0;
;                   f32x4 a0, a1, b0, b1; pg8::unpack8(*(const v4u*)op, a0, a1); pg8::unpack8(*(const v4u*)(op + 128), b0, b1);
;                   a0 = a0 - b0 * lam; a1 = a1 - b1 * lam;
;                   float ss = (a0[0] * a0[0] + a0[1] * a0[1]) + (a0[2] * a0[2] + a0[3] * a0[3]) + (a1[0] * a1[0] + a1[1] * a1[1]) + (a1[2] * a1[2] + a1[3] * a1[3]);
;                   ss += __shfl_xor(ss, 1); ss += __shfl_xor(ss, 2); ss += __shfl_xor(ss, 4); ss += __shfl_xor(ss, 8);
;                   const float rn = __builtin_amdgcn_rsqf(ss * (1.0f / 128.0f) + 1e-6f);
;                   *(v4u*)(OC + (size_t)m * 512 + 128 * h + c0) = pg8::pack8(a0 * rn * sg0, a1 * rn * sg1);
;               } }
.LBB0_1363:
	global_load_dwordx2 v[40:41], v38, s[4:5]
	global_load_dwordx4 v[42:45], v39, s[4:5]
	v_add_u32_e32 v38, s12, v38
	v_add_u32_e32 v39, s13, v39
	v_add_co_u32_e32 v4, vcc, 0xffffff00, v14
	v_xor_b32_e32 v29, 0x80000000, v3
	s_nop 0
	v_addc_co_u32_e32 v5, vcc, -1, v15, vcc
	flat_load_dwordx4 v[4:7], v[4:5]
	s_nop 0
	flat_load_dwordx4 v[8:11], v[14:15]
	v_xor_b32_e32 v28, 0x80000000, v2
	s_add_i32 s0, s0, s2
	s_cmpk_gt_i32 s0, 0x3fff
	v_lshl_add_u64 v[14:15], v[14:15], 0, s[6:7]
	s_waitcnt vmcnt(0) lgkmcnt(0)
	v_lshlrev_b32_e32 v30, 16, v4
	v_and_b32_e32 v31, 0xffff0000, v4
	v_lshlrev_b32_e32 v4, 16, v5
	v_and_b32_e32 v5, 0xffff0000, v5
	v_lshlrev_b32_e32 v34, 16, v8
	v_and_b32_e32 v35, 0xffff0000, v8
	v_lshlrev_b32_e32 v8, 16, v9
	v_and_b32_e32 v9, 0xffff0000, v9
	v_lshlrev_b32_e32 v32, 16, v6
	v_and_b32_e32 v33, 0xffff0000, v6
	v_lshlrev_b32_e32 v6, 16, v7
	v_and_b32_e32 v7, 0xffff0000, v7
	v_lshlrev_b32_e32 v36, 16, v10
	v_and_b32_e32 v37, 0xffff0000, v10
	v_lshlrev_b32_e32 v10, 16, v11
	v_and_b32_e32 v11, 0xffff0000, v11
	v_add_f32_e32 v40, v40, v42
	v_add_f32_e32 v41, v41, v44
	v_add_f32_e32 v40, v40, v43
	v_add_f32_e32 v41, v41, v45
	v_rcp_f32_e32 v40, v40
	v_rcp_f32_e32 v41, v41
	s_nop 0
	v_cndmask_b32_e64 v40, 1.0, v40, s[14:15]
	v_cndmask_b32_e64 v41, 1.0, v41, s[14:15]
	v_mul_f32_e32 v30, v30, v40
	v_mul_f32_e32 v31, v31, v40
	v_mul_f32_e32 v4, v4, v40
	v_mul_f32_e32 v5, v5, v40
	v_mul_f32_e32 v32, v32, v40
	v_mul_f32_e32 v33, v33, v40
	v_mul_f32_e32 v6, v6, v40
	v_mul_f32_e32 v7, v7, v40
	v_mul_f32_e32 v34, v34, v41
	v_mul_f32_e32 v35, v35, v41
	v_mul_f32_e32 v8, v8, v41
	v_mul_f32_e32 v9, v9, v41
	v_mul_f32_e32 v36, v36, v41
	v_mul_f32_e32 v37, v37, v41
	v_mul_f32_e32 v10, v10, v41
	v_mul_f32_e32 v11, v11, v41
	v_pk_fma_f32 v[30:31], v[18:19], v[34:35], v[30:31] neg_lo:[1,0,0] neg_hi:[1,0,0]
	v_pk_fma_f32 v[4:5], v[28:29], v[8:9], v[4:5]
	v_pk_fma_f32 v[8:9], v[18:19], v[36:37], v[32:33] neg_lo:[1,0,0] neg_hi:[1,0,0]
	v_pk_fma_f32 v[6:7], v[28:29], v[10:11], v[6:7]
	v_pk_mul_f32 v[10:11], v[4:5], v[4:5]
	v_pk_mul_f32 v[28:29], v[30:31], v[30:31]
	v_pk_mul_f32 v[32:33], v[6:7], v[6:7]
	v_pk_mul_f32 v[34:35], v[8:9], v[8:9]
	v_pk_mov_b32 v[36:37], v[28:29], v[10:11] op_sel:[1,0]
	v_mov_b32_e32 v29, v11
	v_mov_b32_e32 v10, v32
	v_mov_b32_e32 v11, v34
	v_mov_b32_e32 v34, v33
	v_pk_add_f32 v[28:29], v[36:37], v[28:29]
	v_pk_add_f32 v[10:11], v[10:11], v[34:35]
	v_add_f32_e32 v28, v28, v29
	v_add_f32_e32 v11, v11, v28
	v_add_f32_e32 v10, v10, v11
	ds_bpermute_b32 v11, v24, v10
	s_waitcnt lgkmcnt(0)
	v_add_f32_e32 v10, v10, v11
	ds_bpermute_b32 v11, v25, v10
	s_waitcnt lgkmcnt(0)
	v_add_f32_e32 v10, v10, v11
	ds_bpermute_b32 v11, v26, v10
	s_waitcnt lgkmcnt(0)
	v_add_f32_e32 v10, v10, v11
	ds_bpermute_b32 v11, v27, v10
	s_waitcnt lgkmcnt(0)
	v_add_f32_e32 v10, v10, v11
	v_fmamk_f32 v10, v10, 0x3c000000, v231
	v_rsq_f32_e32 v10, v10
	s_nop 0
	v_pk_mul_f32 v[28:29], v[30:31], v[10:11] op_sel_hi:[1,0]
	v_pk_mul_f32 v[4:5], v[4:5], v[10:11] op_sel_hi:[1,0]
	v_pk_mul_f32 v[8:9], v[8:9], v[10:11] op_sel_hi:[1,0]
	v_pk_mul_f32 v[6:7], v[6:7], v[10:11] op_sel_hi:[1,0]
	v_pk_mul_f32 v[10:11], v[12:13], v[4:5]
	v_pk_mul_f32 v[4:5], v[0:1], v[28:29]
	v_pk_mul_f32 v[28:29], v[22:23], v[6:7]
	v_pk_mul_f32 v[6:7], v[20:21], v[8:9]
	v_cvt_pk_bf16_f32 v4, v4, v5
	v_cvt_pk_bf16_f32 v5, v10, v11
	v_cvt_pk_bf16_f32 v6, v6, v7
	v_cvt_pk_bf16_f32 v7, v28, v29
	flat_store_dwordx4 v[16:17], v[4:7]
	v_lshl_add_u64 v[16:17], v[16:17], 0, s[8:9]
	s_cbranch_scc0 .LBB0_1363
